# attention item epilogue: the 15 gate groups load their z pair and weight quad three groups early into rotating temporaries, waits recounted
# speedup vs baseline: 1.0072x; 1.0027x over previous
.LBB0_83:
	ds_bpermute_b32 v0, v176, v69
	s_waitcnt lgkmcnt(0)
	v_add_f32_e32 v0, v69, v0
	v_div_scale_f32 v1, s[2:3], v0, v0, 1.0
	v_rcp_f32_e32 v2, v1
	s_nop 0
	v_fma_f32 v68, -v1, v2, 1.0
	v_fmac_f32_e32 v2, v68, v2
	v_div_scale_f32 v68, vcc, 1.0, v0, 1.0
	v_mul_f32_e32 v69, v68, v2
	v_fma_f32 v70, -v1, v69, v68
	v_fmac_f32_e32 v69, v70, v2
	v_fma_f32 v1, -v1, v69, v68
	v_div_fmas_f32 v1, v1, v2, v69
	v_div_fixup_f32 v0, v1, v0, 1.0
	v_mul_f32_e32 v72, v159, v0
	global_load_dwordx2 v[136:137], v[144:145], off
	global_load_dwordx2 v[76:77], v[144:145], off offset:16
	global_load_dwordx2 v[80:81], v[144:145], off offset:32
	global_load_dwordx2 v[84:85], v[144:145], off offset:48
	global_load_dwordx2 v[88:89], v[144:145], off offset:64
	global_load_dwordx2 v[92:93], v[144:145], off offset:80
	global_load_dwordx2 v[96:97], v[144:145], off offset:96
	global_load_dwordx2 v[100:101], v[144:145], off offset:112
	global_load_dwordx2 v[104:105], v[144:145], off offset:128
	global_load_dwordx2 v[108:109], v[144:145], off offset:144
	global_load_dwordx2 v[116:117], v[144:145], off offset:160
	global_load_dwordx2 v[120:121], v[144:145], off offset:176
	global_load_dwordx2 v[124:125], v[144:145], off offset:192
	global_load_dwordx2 v[128:129], v[144:145], off offset:208
	global_load_dwordx2 v[132:133], v[144:145], off offset:224
	global_load_dwordx2 v[0:1], v[144:145], off offset:240
	v_lshlrev_b32_e32 v2, 1, v146
	v_lshl_add_u64 v[70:71], v[148:149], 0, v[2:3]
	s_waitcnt vmcnt(0)
	v_lshlrev_b32_e32 v134, 16, v136
	v_and_b32_e32 v135, 0xffff0000, v136
	v_lshlrev_b32_e32 v136, 16, v137
	v_and_b32_e32 v137, 0xffff0000, v137
	v_lshlrev_b32_e32 v74, 16, v76
	v_and_b32_e32 v75, 0xffff0000, v76
	v_lshlrev_b32_e32 v76, 16, v77
	v_and_b32_e32 v77, 0xffff0000, v77
	v_lshlrev_b32_e32 v78, 16, v80
	v_and_b32_e32 v79, 0xffff0000, v80
	v_lshlrev_b32_e32 v80, 16, v81
	v_and_b32_e32 v81, 0xffff0000, v81
	v_lshlrev_b32_e32 v82, 16, v84
	v_and_b32_e32 v83, 0xffff0000, v84
	v_lshlrev_b32_e32 v84, 16, v85
	v_and_b32_e32 v85, 0xffff0000, v85
	v_lshlrev_b32_e32 v86, 16, v88
	v_and_b32_e32 v87, 0xffff0000, v88
	v_lshlrev_b32_e32 v88, 16, v89
	v_and_b32_e32 v89, 0xffff0000, v89
	v_lshlrev_b32_e32 v90, 16, v92
	v_and_b32_e32 v91, 0xffff0000, v92
	v_lshlrev_b32_e32 v92, 16, v93
	v_and_b32_e32 v93, 0xffff0000, v93
	v_lshlrev_b32_e32 v94, 16, v96
	v_and_b32_e32 v95, 0xffff0000, v96
	v_lshlrev_b32_e32 v96, 16, v97
	v_and_b32_e32 v97, 0xffff0000, v97
	v_lshlrev_b32_e32 v98, 16, v100
	v_and_b32_e32 v99, 0xffff0000, v100
	v_lshlrev_b32_e32 v100, 16, v101
	v_and_b32_e32 v101, 0xffff0000, v101
	v_lshlrev_b32_e32 v102, 16, v104
	v_and_b32_e32 v103, 0xffff0000, v104
	v_lshlrev_b32_e32 v104, 16, v105
	v_and_b32_e32 v105, 0xffff0000, v105
	v_lshlrev_b32_e32 v106, 16, v108
	v_and_b32_e32 v107, 0xffff0000, v108
	v_lshlrev_b32_e32 v108, 16, v109
	v_and_b32_e32 v109, 0xffff0000, v109
	v_lshlrev_b32_e32 v110, 16, v116
	v_and_b32_e32 v111, 0xffff0000, v116
	v_lshlrev_b32_e32 v116, 16, v117
	v_and_b32_e32 v117, 0xffff0000, v117
	v_lshlrev_b32_e32 v118, 16, v120
	v_and_b32_e32 v119, 0xffff0000, v120
	v_lshlrev_b32_e32 v120, 16, v121
	v_and_b32_e32 v121, 0xffff0000, v121
	v_lshlrev_b32_e32 v122, 16, v124
	v_and_b32_e32 v123, 0xffff0000, v124
	v_lshlrev_b32_e32 v124, 16, v125
	v_and_b32_e32 v125, 0xffff0000, v125
	v_lshlrev_b32_e32 v126, 16, v128
	v_and_b32_e32 v127, 0xffff0000, v128
	v_lshlrev_b32_e32 v128, 16, v129
	v_and_b32_e32 v129, 0xffff0000, v129
	v_lshlrev_b32_e32 v130, 16, v132
	v_and_b32_e32 v131, 0xffff0000, v132
	v_lshlrev_b32_e32 v132, 16, v133
	v_and_b32_e32 v133, 0xffff0000, v133
	v_lshlrev_b32_e32 v68, 16, v0
	v_and_b32_e32 v69, 0xffff0000, v0
	v_pk_fma_f32 v[68:69], v[16:17], v[72:73], v[68:69] op_sel_hi:[1,0,1] neg_lo:[1,0,0] neg_hi:[1,0,0]
	global_load_dwordx2 v[16:17], v[70:71], off offset:2048
	v_lshlrev_b32_e32 v0, 16, v1
	v_and_b32_e32 v1, 0xffff0000, v1
	v_pk_fma_f32 v[0:1], v[18:19], v[72:73], v[0:1] op_sel_hi:[1,0,1] neg_lo:[1,0,0] neg_hi:[1,0,0]
	v_lshlrev_b32_e32 v73, 2, v146
	v_pk_fma_f32 v[134:135], v[52:53], v[72:73], v[134:135] op_sel_hi:[1,0,1] neg_lo:[1,0,0] neg_hi:[1,0,0]
	v_pk_fma_f32 v[136:137], v[54:55], v[72:73], v[136:137] op_sel_hi:[1,0,1] neg_lo:[1,0,0] neg_hi:[1,0,0]
	v_pk_mul_f32 v[142:143], v[134:135], v[134:135]
	v_pk_mul_f32 v[140:141], v[136:137], v[136:137]
	v_pk_fma_f32 v[150:151], v[56:57], v[72:73], v[74:75] op_sel_hi:[1,0,1] neg_lo:[1,0,0] neg_hi:[1,0,0]
	v_pk_fma_f32 v[74:75], v[62:63], v[72:73], v[80:81] op_sel_hi:[1,0,1] neg_lo:[1,0,0] neg_hi:[1,0,0]
	v_pk_mul_f32 v[154:155], v[150:151], v[150:151]
	v_pk_mul_f32 v[80:81], v[74:75], v[74:75]
	v_pk_fma_f32 v[64:65], v[64:65], v[72:73], v[82:83] op_sel_hi:[1,0,1] neg_lo:[1,0,0] neg_hi:[1,0,0]
	v_pk_fma_f32 v[66:67], v[66:67], v[72:73], v[84:85] op_sel_hi:[1,0,1] neg_lo:[1,0,0] neg_hi:[1,0,0]
	v_pk_mul_f32 v[82:83], v[64:65], v[64:65]
	v_pk_mul_f32 v[84:85], v[66:67], v[66:67]
	v_pk_fma_f32 v[62:63], v[36:37], v[72:73], v[86:87] op_sel_hi:[1,0,1] neg_lo:[1,0,0] neg_hi:[1,0,0]
	v_pk_fma_f32 v[56:57], v[42:43], v[72:73], v[92:93] op_sel_hi:[1,0,1] neg_lo:[1,0,0] neg_hi:[1,0,0]
	v_pk_mul_f32 v[86:87], v[62:63], v[62:63]
	v_pk_mul_f32 v[92:93], v[56:57], v[56:57]
	v_pk_fma_f32 v[42:43], v[20:21], v[72:73], v[102:103] op_sel_hi:[1,0,1] neg_lo:[1,0,0] neg_hi:[1,0,0]
	v_pk_fma_f32 v[36:37], v[26:27], v[72:73], v[108:109] op_sel_hi:[1,0,1] neg_lo:[1,0,0] neg_hi:[1,0,0]
	v_pk_fma_f32 v[28:29], v[28:29], v[72:73], v[110:111] op_sel_hi:[1,0,1] neg_lo:[1,0,0] neg_hi:[1,0,0]
	v_pk_mul_f32 v[102:103], v[36:37], v[36:37]
	v_pk_mul_f32 v[108:109], v[28:29], v[28:29]
	v_pk_fma_f32 v[30:31], v[30:31], v[72:73], v[116:117] op_sel_hi:[1,0,1] neg_lo:[1,0,0] neg_hi:[1,0,0]
	v_pk_fma_f32 v[26:27], v[32:33], v[72:73], v[118:119] op_sel_hi:[1,0,1] neg_lo:[1,0,0] neg_hi:[1,0,0]
	v_pk_fma_f32 v[20:21], v[6:7], v[72:73], v[124:125] op_sel_hi:[1,0,1] neg_lo:[1,0,0] neg_hi:[1,0,0]
	v_pk_mul_f32 v[32:33], v[26:27], v[26:27]
	v_pk_mul_f32 v[110:111], v[20:21], v[20:21]
	v_pk_fma_f32 v[8:9], v[8:9], v[72:73], v[126:127] op_sel_hi:[1,0,1] neg_lo:[1,0,0] neg_hi:[1,0,0]
	v_pk_fma_f32 v[10:11], v[10:11], v[72:73], v[128:129] op_sel_hi:[1,0,1] neg_lo:[1,0,0] neg_hi:[1,0,0]
	v_pk_fma_f32 v[6:7], v[12:13], v[72:73], v[130:131] op_sel_hi:[1,0,1] neg_lo:[1,0,0] neg_hi:[1,0,0]
	v_pk_mul_f32 v[118:119], v[10:11], v[10:11]
	v_pk_mul_f32 v[12:13], v[6:7], v[6:7]
	v_pk_mul_f32 v[112:113], v[68:69], v[68:69]
	v_pk_mul_f32 v[114:115], v[0:1], v[0:1]
	s_waitcnt vmcnt(0)
	v_lshlrev_b32_e32 v2, 16, v16
	v_and_b32_e32 v138, 0xffff0000, v16
	v_mul_f32_e32 v52, 0xbfb8aa3b, v2
	v_mul_f32_e32 v53, 0xbfb8aa3b, v138
	v_exp_f32_e32 v52, v52
	v_exp_f32_e32 v53, v53
	v_lshlrev_b32_e32 v146, 16, v17
	v_and_b32_e32 v147, 0xffff0000, v17
	global_load_dwordx4 v[16:19], v73, s[38:39]
	global_load_dwordx2 v[204:205], v[70:71], off offset:2064
	global_load_dwordx4 v[216:219], v73, s[38:39] offset:32
	global_load_dwordx2 v[206:207], v[70:71], off offset:2080
	global_load_dwordx4 v[220:223], v73, s[38:39] offset:64
	global_load_dwordx2 v[208:209], v[70:71], off offset:2096
	global_load_dwordx4 v[236:239], v73, s[38:39] offset:96
	v_pk_add_f32 v[52:53], v[52:53], 1.0 op_sel_hi:[1,0]
	s_nop 0
	v_div_scale_f32 v54, s[2:3], v53, v53, v138
	v_rcp_f32_e32 v55, v54
	s_nop 0
	v_fma_f32 v139, -v54, v55, 1.0
	v_fmac_f32_e32 v55, v139, v55
	v_div_scale_f32 v139, vcc, v138, v53, v138
	v_mul_f32_e32 v148, v139, v55
	v_fma_f32 v149, -v54, v148, v139
	v_fmac_f32_e32 v148, v149, v55
	v_fma_f32 v54, -v54, v148, v139
	v_div_fmas_f32 v54, v54, v55, v148
	v_div_fixup_f32 v139, v54, v53, v138
	v_div_scale_f32 v53, s[2:3], v52, v52, v2
	v_rcp_f32_e32 v54, v53
	s_nop 0
	v_fma_f32 v55, -v53, v54, 1.0
	v_fmac_f32_e32 v54, v55, v54
	v_div_scale_f32 v55, vcc, v2, v52, v2
	v_mul_f32_e32 v138, v55, v54
	v_fma_f32 v148, -v53, v138, v55
	v_fmac_f32_e32 v138, v148, v54
	v_fma_f32 v53, -v53, v138, v55
	v_div_fmas_f32 v53, v53, v54, v138
	v_div_fixup_f32 v138, v53, v52, v2
	v_mul_f32_e32 v2, 0xbfb8aa3b, v146
	v_exp_f32_e32 v52, v2
	v_mul_f32_e32 v2, 0xbfb8aa3b, v147
	v_exp_f32_e32 v53, v2
	s_nop 0
	v_pk_add_f32 v[52:53], v[52:53], 1.0 op_sel_hi:[1,0]
	s_nop 0
	v_div_scale_f32 v2, s[2:3], v53, v53, v147
	v_rcp_f32_e32 v54, v2
	s_nop 0
	v_fma_f32 v55, -v2, v54, 1.0
	v_fmac_f32_e32 v54, v55, v54
	v_div_scale_f32 v55, vcc, v147, v53, v147
	v_mul_f32_e32 v148, v55, v54
	v_fma_f32 v149, -v2, v148, v55
	v_fmac_f32_e32 v148, v149, v54
	v_fma_f32 v2, -v2, v148, v55
	v_div_fmas_f32 v2, v2, v54, v148
	v_div_fixup_f32 v149, v2, v53, v147
	v_div_scale_f32 v2, s[2:3], v52, v52, v146
	v_rcp_f32_e32 v53, v2
	s_nop 0
	v_fma_f32 v54, -v2, v53, 1.0
	v_fmac_f32_e32 v53, v54, v53
	v_div_scale_f32 v54, vcc, v146, v52, v146
	v_mul_f32_e32 v55, v54, v53
	v_fma_f32 v147, -v2, v55, v54
	v_fmac_f32_e32 v55, v147, v53
	v_fma_f32 v2, -v2, v55, v54
	v_div_fmas_f32 v2, v2, v53, v55
	v_div_fixup_f32 v148, v2, v52, v146
	v_add_f32_e32 v2, v142, v143
	v_add_f32_e32 v2, v140, v2
	v_add_f32_e32 v2, v141, v2
	v_pk_fma_f32 v[146:147], v[58:59], v[72:73], v[76:77] op_sel_hi:[1,0,1] neg_lo:[1,0,0] neg_hi:[1,0,0]
	v_add_f32_e32 v2, v154, v2
	v_pk_mul_f32 v[152:153], v[146:147], v[146:147]
	v_add_f32_e32 v2, v155, v2
	v_pk_fma_f32 v[76:77], v[60:61], v[72:73], v[78:79] op_sel_hi:[1,0,1] neg_lo:[1,0,0] neg_hi:[1,0,0]
	v_add_f32_e32 v2, v152, v2
	v_pk_mul_f32 v[78:79], v[76:77], v[76:77]
	v_add_f32_e32 v2, v153, v2
	v_add_f32_e32 v2, v78, v2
	v_add_f32_e32 v2, v79, v2
	v_add_f32_e32 v2, v80, v2
	v_add_f32_e32 v2, v81, v2
	v_add_f32_e32 v2, v82, v2
	v_add_f32_e32 v2, v83, v2
	v_add_f32_e32 v2, v84, v2
	v_add_f32_e32 v2, v85, v2
	v_pk_fma_f32 v[60:61], v[38:39], v[72:73], v[88:89] op_sel_hi:[1,0,1] neg_lo:[1,0,0] neg_hi:[1,0,0]
	v_add_f32_e32 v2, v86, v2
	v_pk_mul_f32 v[88:89], v[60:61], v[60:61]
	v_add_f32_e32 v2, v87, v2
	v_pk_fma_f32 v[58:59], v[40:41], v[72:73], v[90:91] op_sel_hi:[1,0,1] neg_lo:[1,0,0] neg_hi:[1,0,0]
	v_add_f32_e32 v2, v88, v2
	v_pk_mul_f32 v[90:91], v[58:59], v[58:59]
	v_add_f32_e32 v2, v89, v2
	v_add_f32_e32 v2, v90, v2
	v_add_f32_e32 v2, v91, v2
	v_pk_fma_f32 v[54:55], v[44:45], v[72:73], v[94:95] op_sel_hi:[1,0,1] neg_lo:[1,0,0] neg_hi:[1,0,0]
	v_add_f32_e32 v2, v92, v2
	v_pk_mul_f32 v[94:95], v[54:55], v[54:55]
	v_add_f32_e32 v2, v93, v2
	v_pk_fma_f32 v[52:53], v[46:47], v[72:73], v[96:97] op_sel_hi:[1,0,1] neg_lo:[1,0,0] neg_hi:[1,0,0]
	v_add_f32_e32 v2, v94, v2
	v_pk_mul_f32 v[96:97], v[52:53], v[52:53]
	v_add_f32_e32 v2, v95, v2
	v_pk_fma_f32 v[46:47], v[48:49], v[72:73], v[98:99] op_sel_hi:[1,0,1] neg_lo:[1,0,0] neg_hi:[1,0,0]
	v_add_f32_e32 v2, v96, v2
	v_pk_mul_f32 v[48:49], v[46:47], v[46:47]
	v_add_f32_e32 v2, v97, v2
	v_pk_fma_f32 v[44:45], v[50:51], v[72:73], v[100:101] op_sel_hi:[1,0,1] neg_lo:[1,0,0] neg_hi:[1,0,0]
	v_add_f32_e32 v2, v48, v2
	v_pk_mul_f32 v[50:51], v[44:45], v[44:45]
	v_add_f32_e32 v2, v49, v2
	v_add_f32_e32 v2, v50, v2
	v_pk_mul_f32 v[100:101], v[42:43], v[42:43]
	v_add_f32_e32 v2, v51, v2
	v_pk_fma_f32 v[40:41], v[22:23], v[72:73], v[104:105] op_sel_hi:[1,0,1] neg_lo:[1,0,0] neg_hi:[1,0,0]
	v_add_f32_e32 v2, v100, v2
	v_pk_mul_f32 v[98:99], v[40:41], v[40:41]
	v_add_f32_e32 v2, v101, v2
	v_pk_fma_f32 v[38:39], v[24:25], v[72:73], v[106:107] op_sel_hi:[1,0,1] neg_lo:[1,0,0] neg_hi:[1,0,0]
	v_add_f32_e32 v2, v98, v2
	v_pk_mul_f32 v[104:105], v[38:39], v[38:39]
	v_add_f32_e32 v2, v99, v2
	v_add_f32_e32 v2, v104, v2
	v_add_f32_e32 v2, v105, v2
	v_add_f32_e32 v2, v102, v2
	v_add_f32_e32 v2, v103, v2
	v_add_f32_e32 v2, v108, v2
	v_pk_mul_f32 v[106:107], v[30:31], v[30:31]
	v_add_f32_e32 v2, v109, v2
	v_add_f32_e32 v2, v106, v2
	v_add_f32_e32 v2, v107, v2
	v_pk_fma_f32 v[24:25], v[34:35], v[72:73], v[120:121] op_sel_hi:[1,0,1] neg_lo:[1,0,0] neg_hi:[1,0,0]
	v_add_f32_e32 v2, v32, v2
	v_pk_mul_f32 v[34:35], v[24:25], v[24:25]
	v_add_f32_e32 v2, v33, v2
	v_pk_fma_f32 v[22:23], v[4:5], v[72:73], v[122:123] op_sel_hi:[1,0,1] neg_lo:[1,0,0] neg_hi:[1,0,0]
	v_add_f32_e32 v2, v34, v2
	v_pk_mul_f32 v[116:117], v[22:23], v[22:23]
	v_add_f32_e32 v2, v35, v2
	v_add_f32_e32 v2, v116, v2
	v_add_f32_e32 v2, v117, v2
	v_add_f32_e32 v2, v110, v2
	v_pk_mul_f32 v[120:121], v[8:9], v[8:9]
	v_add_f32_e32 v2, v111, v2
	v_add_f32_e32 v2, v120, v2
	v_add_f32_e32 v2, v121, v2
	v_add_f32_e32 v2, v118, v2
	v_add_f32_e32 v2, v119, v2
	v_pk_fma_f32 v[4:5], v[14:15], v[72:73], v[132:133] op_sel_hi:[1,0,1] neg_lo:[1,0,0] neg_hi:[1,0,0]
	v_add_f32_e32 v2, v12, v2
	v_pk_mul_f32 v[14:15], v[4:5], v[4:5]
	v_add_f32_e32 v2, v13, v2
	v_add_f32_e32 v2, v14, v2
	v_add_f32_e32 v2, v15, v2
	v_add_f32_e32 v2, v112, v2
	v_add_f32_e32 v2, v113, v2
	v_add_f32_e32 v2, v114, v2
	v_add_f32_e32 v2, v115, v2
	ds_bpermute_b32 v12, v176, v2
	s_waitcnt lgkmcnt(0)
	v_add_f32_e32 v2, v2, v12
	v_mov_b32_e32 v12, 0x3727c5ac
	v_fmamk_f32 v2, v2, 0x3c000000, v12
	v_cmp_gt_f32_e32 vcc, s50, v2
	v_mul_f32_e32 v12, 0x4b800000, v2
	s_nop 0
	v_cndmask_b32_e32 v2, v2, v12, vcc
	v_rsq_f32_e32 v2, v2
	s_nop 0
	v_mul_f32_e32 v12, 0x45800000, v2
	v_cndmask_b32_e32 v2, v2, v12, vcc
	v_mul_f32_e32 v2, v161, v2
	v_pk_mul_f32 v[12:13], v[134:135], v[2:3] op_sel_hi:[1,0]
	v_pk_mul_f32 v[14:15], v[136:137], v[2:3] op_sel_hi:[1,0]
	s_waitcnt vmcnt(0)
	v_pk_mul_f32 v[12:13], v[16:17], v[12:13]
	v_pk_mul_f32 v[14:15], v[18:19], v[14:15]
	v_pk_mul_f32 v[12:13], v[138:139], v[12:13]
	v_pk_mul_f32 v[14:15], v[148:149], v[14:15]
	v_cvt_pk_bf16_f32 v12, v12, v13
	v_cvt_pk_bf16_f32 v13, v14, v15
	global_store_dwordx2 v[144:145], v[12:13], off
	global_load_dwordx2 v[202:203], v[70:71], off offset:2112
	global_load_dwordx4 v[212:215], v73, s[38:39] offset:128
	s_nop 0
	v_pk_mul_f32 v[32:33], v[150:151], v[2:3] op_sel_hi:[1, 0]
	v_pk_mul_f32 v[28:29], v[28:29], v[2:3] op_sel_hi:[1, 0]
	v_pk_mul_f32 v[26:27], v[26:27], v[2:3] op_sel_hi:[1, 0]
	v_pk_mul_f32 v[22:23], v[22:23], v[2:3] op_sel_hi:[1, 0]
	v_pk_mul_f32 v[8:9], v[8:9], v[2:3] op_sel_hi:[1, 0]
	v_pk_mul_f32 v[10:11], v[10:11], v[2:3] op_sel_hi:[1, 0]
	v_pk_mul_f32 v[6:7], v[6:7], v[2:3] op_sel_hi:[1, 0]
	v_pk_mul_f32 v[4:5], v[4:5], v[2:3] op_sel_hi:[1, 0]
	v_pk_mul_f32 v[0:1], v[0:1], v[2:3] op_sel_hi:[1, 0]
	s_waitcnt vmcnt(8)
	v_lshlrev_b32_e32 v34, 16, v204
	v_and_b32_e32 v16, 0xffff0000, v204
	v_mul_f32_e32 v18, 0xbfb8aa3b, v34
	v_mul_f32_e32 v19, 0xbfb8aa3b, v16
	v_exp_f32_e32 v18, v18
	v_exp_f32_e32 v19, v19
	s_waitcnt vmcnt(7)
	v_pk_mul_f32 v[12:13], v[216:217], v[32:33]
	v_pk_add_f32 v[18:19], v[18:19], 1.0 op_sel_hi:[1, 0]
	s_nop 0
	v_div_scale_f32 v32, s[2:3], v19, v19, v16
	v_rcp_f32_e32 v33, v32
	s_nop 0
	v_fma_f32 v35, -v32, v33, 1.0
	v_fmac_f32_e32 v33, v35, v33
	v_div_scale_f32 v35, vcc, v16, v19, v16
	v_mul_f32_e32 v48, v35, v33
	v_fma_f32 v49, -v32, v48, v35
	v_fmac_f32_e32 v48, v49, v33
	v_fma_f32 v32, -v32, v48, v35
	v_div_fmas_f32 v32, v32, v33, v48
	v_div_fixup_f32 v19, v32, v19, v16
	v_div_scale_f32 v16, s[2:3], v18, v18, v34
	v_rcp_f32_e32 v32, v16
	s_nop 0
	v_fma_f32 v33, -v16, v32, 1.0
	v_fmac_f32_e32 v32, v33, v32
	v_div_scale_f32 v33, vcc, v34, v18, v34
	v_mul_f32_e32 v35, v33, v32
	v_fma_f32 v48, -v16, v35, v33
	v_fmac_f32_e32 v35, v48, v32
	v_fma_f32 v16, -v16, v35, v33
	v_div_fmas_f32 v16, v16, v32, v35
	v_lshlrev_b32_e32 v32, 16, v205
	v_and_b32_e32 v33, 0xffff0000, v205
	v_div_fixup_f32 v18, v16, v18, v34
	v_mul_f32_e32 v16, 0xbfb8aa3b, v32
	v_mul_f32_e32 v17, 0xbfb8aa3b, v33
	v_exp_f32_e32 v16, v16
	v_exp_f32_e32 v17, v17
	v_pk_mul_f32 v[12:13], v[18:19], v[12:13]
	v_pk_mul_f32 v[18:19], v[146:147], v[2:3] op_sel_hi:[1, 0]
	v_cvt_pk_bf16_f32 v12, v12, v13
	v_pk_add_f32 v[16:17], v[16:17], 1.0 op_sel_hi:[1, 0]
	v_pk_mul_f32 v[14:15], v[218:219], v[18:19]
	v_div_scale_f32 v18, s[2:3], v17, v17, v33
	v_rcp_f32_e32 v19, v18
	s_nop 0
	v_fma_f32 v34, -v18, v19, 1.0
	v_fmac_f32_e32 v19, v34, v19
	v_div_scale_f32 v34, vcc, v33, v17, v33
	v_mul_f32_e32 v35, v34, v19
	v_fma_f32 v48, -v18, v35, v34
	v_fmac_f32_e32 v35, v48, v19
	v_fma_f32 v18, -v18, v35, v34
	v_div_fmas_f32 v18, v18, v19, v35
	v_div_fixup_f32 v17, v18, v17, v33
	v_div_scale_f32 v18, s[2:3], v16, v16, v32
	v_rcp_f32_e32 v19, v18
	s_nop 0
	v_fma_f32 v33, -v18, v19, 1.0
	v_fmac_f32_e32 v19, v33, v19
	v_div_scale_f32 v33, vcc, v32, v16, v32
	v_mul_f32_e32 v34, v33, v19
	v_fma_f32 v35, -v18, v34, v33
	v_fmac_f32_e32 v34, v35, v19
	v_fma_f32 v18, -v18, v34, v33
	v_div_fmas_f32 v18, v18, v19, v34
	v_div_fixup_f32 v16, v18, v16, v32
	v_pk_mul_f32 v[14:15], v[16:17], v[14:15]
	v_pk_mul_f32 v[32:33], v[76:77], v[2:3] op_sel_hi:[1,0]
	v_cvt_pk_bf16_f32 v13, v14, v15
	global_store_dwordx2 v[144:145], v[12:13], off offset:16
	global_load_dwordx2 v[204:205], v[70:71], off offset:2128
	global_load_dwordx4 v[216:219], v73, s[38:39] offset:160
	s_nop 0
	s_waitcnt vmcnt(9)
	v_lshlrev_b32_e32 v34, 16, v206
	v_and_b32_e32 v16, 0xffff0000, v206
	v_mul_f32_e32 v18, 0xbfb8aa3b, v34
	v_mul_f32_e32 v19, 0xbfb8aa3b, v16
	v_exp_f32_e32 v18, v18
	v_exp_f32_e32 v19, v19
	s_waitcnt vmcnt(8)
	v_pk_mul_f32 v[12:13], v[220:221], v[32:33]
	v_pk_add_f32 v[18:19], v[18:19], 1.0 op_sel_hi:[1, 0]
	s_nop 0
	v_div_scale_f32 v32, s[2:3], v19, v19, v16
	v_rcp_f32_e32 v33, v32
	s_nop 0
	v_fma_f32 v35, -v32, v33, 1.0
	v_fmac_f32_e32 v33, v35, v33
	v_div_scale_f32 v35, vcc, v16, v19, v16
	v_mul_f32_e32 v48, v35, v33
	v_fma_f32 v49, -v32, v48, v35
	v_fmac_f32_e32 v48, v49, v33
	v_fma_f32 v32, -v32, v48, v35
	v_div_fmas_f32 v32, v32, v33, v48
	v_div_fixup_f32 v19, v32, v19, v16
	v_div_scale_f32 v16, s[2:3], v18, v18, v34
	v_rcp_f32_e32 v32, v16
	s_nop 0
	v_fma_f32 v33, -v16, v32, 1.0
	v_fmac_f32_e32 v32, v33, v32
	v_div_scale_f32 v33, vcc, v34, v18, v34
	v_mul_f32_e32 v35, v33, v32
	v_fma_f32 v48, -v16, v35, v33
	v_fmac_f32_e32 v35, v48, v32
	v_fma_f32 v16, -v16, v35, v33
	v_div_fmas_f32 v16, v16, v32, v35
	v_lshlrev_b32_e32 v32, 16, v207
	v_and_b32_e32 v33, 0xffff0000, v207
	v_div_fixup_f32 v18, v16, v18, v34
	v_mul_f32_e32 v16, 0xbfb8aa3b, v32
	v_mul_f32_e32 v17, 0xbfb8aa3b, v33
	v_exp_f32_e32 v16, v16
	v_exp_f32_e32 v17, v17
	v_pk_mul_f32 v[12:13], v[18:19], v[12:13]
	v_pk_mul_f32 v[18:19], v[74:75], v[2:3] op_sel_hi:[1, 0]
	v_cvt_pk_bf16_f32 v12, v12, v13
	v_pk_add_f32 v[16:17], v[16:17], 1.0 op_sel_hi:[1, 0]
	v_pk_mul_f32 v[14:15], v[222:223], v[18:19]
	v_div_scale_f32 v18, s[2:3], v17, v17, v33
	v_rcp_f32_e32 v19, v18
	s_nop 0
	v_fma_f32 v34, -v18, v19, 1.0
	v_fmac_f32_e32 v19, v34, v19
	v_div_scale_f32 v34, vcc, v33, v17, v33
	v_mul_f32_e32 v35, v34, v19
	v_fma_f32 v48, -v18, v35, v34
	v_fmac_f32_e32 v35, v48, v19
	v_fma_f32 v18, -v18, v35, v34
	v_div_fmas_f32 v18, v18, v19, v35
	v_div_fixup_f32 v17, v18, v17, v33
	v_div_scale_f32 v18, s[2:3], v16, v16, v32
	v_rcp_f32_e32 v19, v18
	s_nop 0
	v_fma_f32 v33, -v18, v19, 1.0
	v_fmac_f32_e32 v19, v33, v19
	v_div_scale_f32 v33, vcc, v32, v16, v32
	v_mul_f32_e32 v34, v33, v19
	v_fma_f32 v35, -v18, v34, v33
	v_fmac_f32_e32 v34, v35, v19
	v_fma_f32 v18, -v18, v34, v33
	v_div_fmas_f32 v18, v18, v19, v34
	v_div_fixup_f32 v16, v18, v16, v32
	v_pk_mul_f32 v[14:15], v[16:17], v[14:15]
	v_pk_mul_f32 v[32:33], v[64:65], v[2:3] op_sel_hi:[1,0]
	v_cvt_pk_bf16_f32 v13, v14, v15
	global_store_dwordx2 v[144:145], v[12:13], off offset:32
	global_load_dwordx2 v[206:207], v[70:71], off offset:2144
	global_load_dwordx4 v[220:223], v73, s[38:39] offset:192
	s_nop 0
	s_waitcnt vmcnt(10)
	v_lshlrev_b32_e32 v34, 16, v208
	v_and_b32_e32 v16, 0xffff0000, v208
	v_mul_f32_e32 v18, 0xbfb8aa3b, v34
	v_mul_f32_e32 v19, 0xbfb8aa3b, v16
	v_exp_f32_e32 v18, v18
	v_exp_f32_e32 v19, v19
	s_waitcnt vmcnt(9)
	v_pk_mul_f32 v[12:13], v[236:237], v[32:33]
	v_pk_add_f32 v[18:19], v[18:19], 1.0 op_sel_hi:[1, 0]
	s_nop 0
	v_div_scale_f32 v32, s[2:3], v19, v19, v16
	v_rcp_f32_e32 v33, v32
	s_nop 0
	v_fma_f32 v35, -v32, v33, 1.0
	v_fmac_f32_e32 v33, v35, v33
	v_div_scale_f32 v35, vcc, v16, v19, v16
	v_mul_f32_e32 v48, v35, v33
	v_fma_f32 v49, -v32, v48, v35
	v_fmac_f32_e32 v48, v49, v33
	v_fma_f32 v32, -v32, v48, v35
	v_div_fmas_f32 v32, v32, v33, v48
	v_div_fixup_f32 v19, v32, v19, v16
	v_div_scale_f32 v16, s[2:3], v18, v18, v34
	v_rcp_f32_e32 v32, v16
	s_nop 0
	v_fma_f32 v33, -v16, v32, 1.0
	v_fmac_f32_e32 v32, v33, v32
	v_div_scale_f32 v33, vcc, v34, v18, v34
	v_mul_f32_e32 v35, v33, v32
	v_fma_f32 v48, -v16, v35, v33
	v_fmac_f32_e32 v35, v48, v32
	v_fma_f32 v16, -v16, v35, v33
	v_div_fmas_f32 v16, v16, v32, v35
	v_lshlrev_b32_e32 v32, 16, v209
	v_and_b32_e32 v33, 0xffff0000, v209
	v_div_fixup_f32 v18, v16, v18, v34
	v_mul_f32_e32 v16, 0xbfb8aa3b, v32
	v_mul_f32_e32 v17, 0xbfb8aa3b, v33
	v_exp_f32_e32 v16, v16
	v_exp_f32_e32 v17, v17
	v_pk_mul_f32 v[12:13], v[18:19], v[12:13]
	v_pk_mul_f32 v[18:19], v[66:67], v[2:3] op_sel_hi:[1, 0]
	v_cvt_pk_bf16_f32 v12, v12, v13
	v_pk_add_f32 v[16:17], v[16:17], 1.0 op_sel_hi:[1, 0]
	v_pk_mul_f32 v[14:15], v[238:239], v[18:19]
	v_div_scale_f32 v18, s[2:3], v17, v17, v33
	v_rcp_f32_e32 v19, v18
	s_nop 0
	v_fma_f32 v34, -v18, v19, 1.0
	v_fmac_f32_e32 v19, v34, v19
	v_div_scale_f32 v34, vcc, v33, v17, v33
	v_mul_f32_e32 v35, v34, v19
	v_fma_f32 v48, -v18, v35, v34
	v_fmac_f32_e32 v35, v48, v19
	v_fma_f32 v18, -v18, v35, v34
	v_div_fmas_f32 v18, v18, v19, v35
	v_div_fixup_f32 v17, v18, v17, v33
	v_div_scale_f32 v18, s[2:3], v16, v16, v32
	v_rcp_f32_e32 v19, v18
	s_nop 0
	v_fma_f32 v33, -v18, v19, 1.0
	v_fmac_f32_e32 v19, v33, v19
	v_div_scale_f32 v33, vcc, v32, v16, v32
	v_mul_f32_e32 v34, v33, v19
	v_fma_f32 v35, -v18, v34, v33
	v_fmac_f32_e32 v34, v35, v19
	v_fma_f32 v18, -v18, v34, v33
	v_div_fmas_f32 v18, v18, v19, v34
	v_div_fixup_f32 v16, v18, v16, v32
	v_pk_mul_f32 v[14:15], v[16:17], v[14:15]
	v_pk_mul_f32 v[32:33], v[62:63], v[2:3] op_sel_hi:[1,0]
	v_cvt_pk_bf16_f32 v13, v14, v15
	global_store_dwordx2 v[144:145], v[12:13], off offset:48
	global_load_dwordx2 v[208:209], v[70:71], off offset:2160
	global_load_dwordx4 v[236:239], v73, s[38:39] offset:224
	s_nop 0
	s_waitcnt vmcnt(10)
	v_lshlrev_b32_e32 v34, 16, v202
	v_and_b32_e32 v16, 0xffff0000, v202
	v_mul_f32_e32 v18, 0xbfb8aa3b, v34
	v_mul_f32_e32 v19, 0xbfb8aa3b, v16
	v_exp_f32_e32 v18, v18
	v_exp_f32_e32 v19, v19
	s_waitcnt vmcnt(9)
	v_pk_mul_f32 v[12:13], v[212:213], v[32:33]
	v_pk_add_f32 v[18:19], v[18:19], 1.0 op_sel_hi:[1, 0]
	s_nop 0
	v_div_scale_f32 v32, s[2:3], v19, v19, v16
	v_rcp_f32_e32 v33, v32
	s_nop 0
	v_fma_f32 v35, -v32, v33, 1.0
	v_fmac_f32_e32 v33, v35, v33
	v_div_scale_f32 v35, vcc, v16, v19, v16
	v_mul_f32_e32 v48, v35, v33
	v_fma_f32 v49, -v32, v48, v35
	v_fmac_f32_e32 v48, v49, v33
	v_fma_f32 v32, -v32, v48, v35
	v_div_fmas_f32 v32, v32, v33, v48
	v_div_fixup_f32 v19, v32, v19, v16
	v_div_scale_f32 v16, s[2:3], v18, v18, v34
	v_rcp_f32_e32 v32, v16
	s_nop 0
	v_fma_f32 v33, -v16, v32, 1.0
	v_fmac_f32_e32 v32, v33, v32
	v_div_scale_f32 v33, vcc, v34, v18, v34
	v_mul_f32_e32 v35, v33, v32
	v_fma_f32 v48, -v16, v35, v33
	v_fmac_f32_e32 v35, v48, v32
	v_fma_f32 v16, -v16, v35, v33
	v_div_fmas_f32 v16, v16, v32, v35
	v_lshlrev_b32_e32 v32, 16, v203
	v_and_b32_e32 v33, 0xffff0000, v203
	v_div_fixup_f32 v18, v16, v18, v34
	v_mul_f32_e32 v16, 0xbfb8aa3b, v32
	v_mul_f32_e32 v17, 0xbfb8aa3b, v33
	v_exp_f32_e32 v16, v16
	v_exp_f32_e32 v17, v17
	v_pk_mul_f32 v[12:13], v[18:19], v[12:13]
	v_pk_mul_f32 v[18:19], v[60:61], v[2:3] op_sel_hi:[1, 0]
	v_cvt_pk_bf16_f32 v12, v12, v13
	v_pk_add_f32 v[16:17], v[16:17], 1.0 op_sel_hi:[1, 0]
	v_pk_mul_f32 v[14:15], v[214:215], v[18:19]
	v_div_scale_f32 v18, s[2:3], v17, v17, v33
	v_rcp_f32_e32 v19, v18
	s_nop 0
	v_fma_f32 v34, -v18, v19, 1.0
	v_fmac_f32_e32 v19, v34, v19
	v_div_scale_f32 v34, vcc, v33, v17, v33
	v_mul_f32_e32 v35, v34, v19
	v_fma_f32 v48, -v18, v35, v34
	v_fmac_f32_e32 v35, v48, v19
	v_fma_f32 v18, -v18, v35, v34
	v_div_fmas_f32 v18, v18, v19, v35
	v_div_fixup_f32 v17, v18, v17, v33
	v_div_scale_f32 v18, s[2:3], v16, v16, v32
	v_rcp_f32_e32 v19, v18
	s_nop 0
	v_fma_f32 v33, -v18, v19, 1.0
	v_fmac_f32_e32 v19, v33, v19
	v_div_scale_f32 v33, vcc, v32, v16, v32
	v_mul_f32_e32 v34, v33, v19
	v_fma_f32 v35, -v18, v34, v33
	v_fmac_f32_e32 v34, v35, v19
	v_fma_f32 v18, -v18, v34, v33
	v_div_fmas_f32 v18, v18, v19, v34
	v_div_fixup_f32 v16, v18, v16, v32
	v_pk_mul_f32 v[14:15], v[16:17], v[14:15]
	v_pk_mul_f32 v[32:33], v[58:59], v[2:3] op_sel_hi:[1,0]
	v_cvt_pk_bf16_f32 v13, v14, v15
	global_store_dwordx2 v[144:145], v[12:13], off offset:64
	global_load_dwordx2 v[202:203], v[70:71], off offset:2176
	global_load_dwordx4 v[212:215], v73, s[38:39] offset:256
	s_nop 0
	s_waitcnt vmcnt(10)
	v_lshlrev_b32_e32 v34, 16, v204
	v_and_b32_e32 v16, 0xffff0000, v204
	v_mul_f32_e32 v18, 0xbfb8aa3b, v34
	v_mul_f32_e32 v19, 0xbfb8aa3b, v16
	v_exp_f32_e32 v18, v18
	v_exp_f32_e32 v19, v19
	s_waitcnt vmcnt(9)
	v_pk_mul_f32 v[12:13], v[216:217], v[32:33]
	v_pk_add_f32 v[18:19], v[18:19], 1.0 op_sel_hi:[1, 0]
	s_nop 0
	v_div_scale_f32 v32, s[2:3], v19, v19, v16
	v_rcp_f32_e32 v33, v32
	s_nop 0
	v_fma_f32 v35, -v32, v33, 1.0
	v_fmac_f32_e32 v33, v35, v33
	v_div_scale_f32 v35, vcc, v16, v19, v16
	v_mul_f32_e32 v48, v35, v33
	v_fma_f32 v49, -v32, v48, v35
	v_fmac_f32_e32 v48, v49, v33
	v_fma_f32 v32, -v32, v48, v35
	v_div_fmas_f32 v32, v32, v33, v48
	v_div_fixup_f32 v19, v32, v19, v16
	v_div_scale_f32 v16, s[2:3], v18, v18, v34
	v_rcp_f32_e32 v32, v16
	s_nop 0
	v_fma_f32 v33, -v16, v32, 1.0
	v_fmac_f32_e32 v32, v33, v32
	v_div_scale_f32 v33, vcc, v34, v18, v34
	v_mul_f32_e32 v35, v33, v32
	v_fma_f32 v48, -v16, v35, v33
	v_fmac_f32_e32 v35, v48, v32
	v_fma_f32 v16, -v16, v35, v33
	v_div_fmas_f32 v16, v16, v32, v35
	v_lshlrev_b32_e32 v32, 16, v205
	v_and_b32_e32 v33, 0xffff0000, v205
	v_div_fixup_f32 v18, v16, v18, v34
	v_mul_f32_e32 v16, 0xbfb8aa3b, v32
	v_mul_f32_e32 v17, 0xbfb8aa3b, v33
	v_exp_f32_e32 v16, v16
	v_exp_f32_e32 v17, v17
	v_pk_mul_f32 v[12:13], v[18:19], v[12:13]
	v_pk_mul_f32 v[18:19], v[56:57], v[2:3] op_sel_hi:[1, 0]
	v_cvt_pk_bf16_f32 v12, v12, v13
	v_pk_add_f32 v[16:17], v[16:17], 1.0 op_sel_hi:[1, 0]
	v_pk_mul_f32 v[14:15], v[218:219], v[18:19]
	v_div_scale_f32 v18, s[2:3], v17, v17, v33
	v_rcp_f32_e32 v19, v18
	s_nop 0
	v_fma_f32 v34, -v18, v19, 1.0
	v_fmac_f32_e32 v19, v34, v19
	v_div_scale_f32 v34, vcc, v33, v17, v33
	v_mul_f32_e32 v35, v34, v19
	v_fma_f32 v48, -v18, v35, v34
	v_fmac_f32_e32 v35, v48, v19
	v_fma_f32 v18, -v18, v35, v34
	v_div_fmas_f32 v18, v18, v19, v35
	v_div_fixup_f32 v17, v18, v17, v33
	v_div_scale_f32 v18, s[2:3], v16, v16, v32
	v_rcp_f32_e32 v19, v18
	s_nop 0
	v_fma_f32 v33, -v18, v19, 1.0
	v_fmac_f32_e32 v19, v33, v19
	v_div_scale_f32 v33, vcc, v32, v16, v32
	v_mul_f32_e32 v34, v33, v19
	v_fma_f32 v35, -v18, v34, v33
	v_fmac_f32_e32 v34, v35, v19
	v_fma_f32 v18, -v18, v34, v33
	v_div_fmas_f32 v18, v18, v19, v34
	v_div_fixup_f32 v16, v18, v16, v32
	v_pk_mul_f32 v[14:15], v[14:15], v[16:17]
	v_pk_mul_f32 v[32:33], v[54:55], v[2:3] op_sel_hi:[1,0]
	v_cvt_pk_bf16_f32 v13, v14, v15
	global_store_dwordx2 v[144:145], v[12:13], off offset:80
	global_load_dwordx2 v[204:205], v[70:71], off offset:2192
	global_load_dwordx4 v[216:219], v73, s[38:39] offset:288
	s_nop 0
	s_waitcnt vmcnt(10)
	v_lshlrev_b32_e32 v34, 16, v206
	v_and_b32_e32 v16, 0xffff0000, v206
	v_mul_f32_e32 v18, 0xbfb8aa3b, v34
	v_mul_f32_e32 v19, 0xbfb8aa3b, v16
	v_exp_f32_e32 v18, v18
	v_exp_f32_e32 v19, v19
	s_waitcnt vmcnt(9)
	v_pk_mul_f32 v[12:13], v[32:33], v[220:221]
	v_pk_add_f32 v[18:19], v[18:19], 1.0 op_sel_hi:[1, 0]
	s_nop 0
	v_div_scale_f32 v32, s[2:3], v19, v19, v16
	v_rcp_f32_e32 v33, v32
	s_nop 0
	v_fma_f32 v35, -v32, v33, 1.0
	v_fmac_f32_e32 v33, v35, v33
	v_div_scale_f32 v35, vcc, v16, v19, v16
	v_mul_f32_e32 v48, v35, v33
	v_fma_f32 v49, -v32, v48, v35
	v_fmac_f32_e32 v48, v49, v33
	v_fma_f32 v32, -v32, v48, v35
	v_div_fmas_f32 v32, v32, v33, v48
	v_div_fixup_f32 v19, v32, v19, v16
	v_div_scale_f32 v16, s[2:3], v18, v18, v34
	v_rcp_f32_e32 v32, v16
	s_nop 0
	v_fma_f32 v33, -v16, v32, 1.0
	v_fmac_f32_e32 v32, v33, v32
	v_div_scale_f32 v33, vcc, v34, v18, v34
	v_mul_f32_e32 v35, v33, v32
	v_fma_f32 v48, -v16, v35, v33
	v_fmac_f32_e32 v35, v48, v32
	v_fma_f32 v16, -v16, v35, v33
	v_div_fmas_f32 v16, v16, v32, v35
	v_lshlrev_b32_e32 v32, 16, v207
	v_and_b32_e32 v33, 0xffff0000, v207
	v_div_fixup_f32 v18, v16, v18, v34
	v_mul_f32_e32 v16, 0xbfb8aa3b, v32
	v_mul_f32_e32 v17, 0xbfb8aa3b, v33
	v_exp_f32_e32 v16, v16
	v_exp_f32_e32 v17, v17
	v_pk_mul_f32 v[12:13], v[12:13], v[18:19]
	v_pk_mul_f32 v[18:19], v[52:53], v[2:3] op_sel_hi:[1, 0]
	v_cvt_pk_bf16_f32 v12, v12, v13
	v_pk_add_f32 v[16:17], v[16:17], 1.0 op_sel_hi:[1, 0]
	v_pk_mul_f32 v[14:15], v[18:19], v[222:223]
	v_div_scale_f32 v18, s[2:3], v17, v17, v33
	v_rcp_f32_e32 v19, v18
	s_nop 0
	v_fma_f32 v34, -v18, v19, 1.0
	v_fmac_f32_e32 v19, v34, v19
	v_div_scale_f32 v34, vcc, v33, v17, v33
	v_mul_f32_e32 v35, v34, v19
	v_fma_f32 v48, -v18, v35, v34
	v_fmac_f32_e32 v35, v48, v19
	v_fma_f32 v18, -v18, v35, v34
	v_div_fmas_f32 v18, v18, v19, v35
	v_div_fixup_f32 v17, v18, v17, v33
	v_div_scale_f32 v18, s[2:3], v16, v16, v32
	v_rcp_f32_e32 v19, v18
	s_nop 0
	v_fma_f32 v33, -v18, v19, 1.0
	v_fmac_f32_e32 v19, v33, v19
	v_div_scale_f32 v33, vcc, v32, v16, v32
	v_mul_f32_e32 v34, v33, v19
	v_fma_f32 v35, -v18, v34, v33
	v_fmac_f32_e32 v34, v35, v19
	v_fma_f32 v18, -v18, v34, v33
	v_div_fmas_f32 v18, v18, v19, v34
	v_div_fixup_f32 v16, v18, v16, v32
	v_pk_mul_f32 v[14:15], v[14:15], v[16:17]
	v_pk_mul_f32 v[32:33], v[46:47], v[2:3] op_sel_hi:[1,0]
	v_cvt_pk_bf16_f32 v13, v14, v15
	global_store_dwordx2 v[144:145], v[12:13], off offset:96
	global_load_dwordx2 v[206:207], v[70:71], off offset:2208
	global_load_dwordx4 v[220:223], v73, s[38:39] offset:320
	s_nop 0
	s_waitcnt vmcnt(10)
	v_lshlrev_b32_e32 v34, 16, v208
	v_and_b32_e32 v16, 0xffff0000, v208
	v_mul_f32_e32 v18, 0xbfb8aa3b, v34
	v_mul_f32_e32 v19, 0xbfb8aa3b, v16
	v_exp_f32_e32 v18, v18
	v_exp_f32_e32 v19, v19
	s_waitcnt vmcnt(9)
	v_pk_mul_f32 v[12:13], v[32:33], v[236:237]
	v_pk_add_f32 v[18:19], v[18:19], 1.0 op_sel_hi:[1, 0]
	s_nop 0
	v_div_scale_f32 v32, s[2:3], v19, v19, v16
	v_rcp_f32_e32 v33, v32
	s_nop 0
	v_fma_f32 v35, -v32, v33, 1.0
	v_fmac_f32_e32 v33, v35, v33
	v_div_scale_f32 v35, vcc, v16, v19, v16
	v_mul_f32_e32 v46, v35, v33
	v_fma_f32 v47, -v32, v46, v35
	v_fmac_f32_e32 v46, v47, v33
	v_fma_f32 v32, -v32, v46, v35
	v_div_fmas_f32 v32, v32, v33, v46
	v_div_fixup_f32 v19, v32, v19, v16
	v_div_scale_f32 v16, s[2:3], v18, v18, v34
	v_rcp_f32_e32 v32, v16
	s_nop 0
	v_fma_f32 v33, -v16, v32, 1.0
	v_fmac_f32_e32 v32, v33, v32
	v_div_scale_f32 v33, vcc, v34, v18, v34
	v_mul_f32_e32 v35, v33, v32
	v_fma_f32 v46, -v16, v35, v33
	v_fmac_f32_e32 v35, v46, v32
	v_fma_f32 v16, -v16, v35, v33
	v_div_fmas_f32 v16, v16, v32, v35
	v_lshlrev_b32_e32 v32, 16, v209
	v_and_b32_e32 v33, 0xffff0000, v209
	v_div_fixup_f32 v18, v16, v18, v34
	v_mul_f32_e32 v16, 0xbfb8aa3b, v32
	v_mul_f32_e32 v17, 0xbfb8aa3b, v33
	v_exp_f32_e32 v16, v16
	v_exp_f32_e32 v17, v17
	v_pk_mul_f32 v[12:13], v[12:13], v[18:19]
	v_pk_mul_f32 v[18:19], v[44:45], v[2:3] op_sel_hi:[1, 0]
	v_cvt_pk_bf16_f32 v12, v12, v13
	v_pk_add_f32 v[16:17], v[16:17], 1.0 op_sel_hi:[1, 0]
	v_pk_mul_f32 v[14:15], v[18:19], v[238:239]
	v_div_scale_f32 v18, s[2:3], v17, v17, v33
	v_rcp_f32_e32 v19, v18
	s_nop 0
	v_fma_f32 v34, -v18, v19, 1.0
	v_fmac_f32_e32 v19, v34, v19
	v_div_scale_f32 v34, vcc, v33, v17, v33
	v_mul_f32_e32 v35, v34, v19
	v_fma_f32 v44, -v18, v35, v34
	v_fmac_f32_e32 v35, v44, v19
	v_fma_f32 v18, -v18, v35, v34
	v_div_fmas_f32 v18, v18, v19, v35
	v_div_fixup_f32 v17, v18, v17, v33
	v_div_scale_f32 v18, s[2:3], v16, v16, v32
	v_rcp_f32_e32 v19, v18
	s_nop 0
	v_fma_f32 v33, -v18, v19, 1.0
	v_fmac_f32_e32 v19, v33, v19
	v_div_scale_f32 v33, vcc, v32, v16, v32
	v_mul_f32_e32 v34, v33, v19
	v_fma_f32 v35, -v18, v34, v33
	v_fmac_f32_e32 v34, v35, v19
	v_fma_f32 v18, -v18, v34, v33
	v_div_fmas_f32 v18, v18, v19, v34
	v_div_fixup_f32 v16, v18, v16, v32
	v_pk_mul_f32 v[14:15], v[14:15], v[16:17]
	v_pk_mul_f32 v[32:33], v[42:43], v[2:3] op_sel_hi:[1,0]
	v_cvt_pk_bf16_f32 v13, v14, v15
	global_store_dwordx2 v[144:145], v[12:13], off offset:112
	global_load_dwordx2 v[208:209], v[70:71], off offset:2224
	global_load_dwordx4 v[236:239], v73, s[38:39] offset:352
	s_nop 0
	s_waitcnt vmcnt(10)
	v_lshlrev_b32_e32 v34, 16, v202
	v_and_b32_e32 v16, 0xffff0000, v202
	v_mul_f32_e32 v18, 0xbfb8aa3b, v34
	v_mul_f32_e32 v19, 0xbfb8aa3b, v16
	v_exp_f32_e32 v18, v18
	v_exp_f32_e32 v19, v19
	s_waitcnt vmcnt(9)
	v_pk_mul_f32 v[12:13], v[32:33], v[212:213]
	v_pk_add_f32 v[18:19], v[18:19], 1.0 op_sel_hi:[1, 0]
	s_nop 0
	v_div_scale_f32 v32, s[2:3], v19, v19, v16
	v_rcp_f32_e32 v33, v32
	s_nop 0
	v_fma_f32 v35, -v32, v33, 1.0
	v_fmac_f32_e32 v33, v35, v33
	v_div_scale_f32 v35, vcc, v16, v19, v16
	v_mul_f32_e32 v42, v35, v33
	v_fma_f32 v43, -v32, v42, v35
	v_fmac_f32_e32 v42, v43, v33
	v_fma_f32 v32, -v32, v42, v35
	v_div_fmas_f32 v32, v32, v33, v42
	v_div_fixup_f32 v19, v32, v19, v16
	v_div_scale_f32 v16, s[2:3], v18, v18, v34
	v_rcp_f32_e32 v32, v16
	s_nop 0
	v_fma_f32 v33, -v16, v32, 1.0
	v_fmac_f32_e32 v32, v33, v32
	v_div_scale_f32 v33, vcc, v34, v18, v34
	v_mul_f32_e32 v35, v33, v32
	v_fma_f32 v42, -v16, v35, v33
	v_fmac_f32_e32 v35, v42, v32
	v_fma_f32 v16, -v16, v35, v33
	v_div_fmas_f32 v16, v16, v32, v35
	v_lshlrev_b32_e32 v32, 16, v203
	v_and_b32_e32 v33, 0xffff0000, v203
	v_div_fixup_f32 v18, v16, v18, v34
	v_mul_f32_e32 v16, 0xbfb8aa3b, v32
	v_mul_f32_e32 v17, 0xbfb8aa3b, v33
	v_exp_f32_e32 v16, v16
	v_exp_f32_e32 v17, v17
	v_pk_mul_f32 v[12:13], v[12:13], v[18:19]
	v_pk_mul_f32 v[18:19], v[40:41], v[2:3] op_sel_hi:[1, 0]
	v_cvt_pk_bf16_f32 v12, v12, v13
	v_pk_add_f32 v[16:17], v[16:17], 1.0 op_sel_hi:[1, 0]
	v_pk_mul_f32 v[14:15], v[18:19], v[214:215]
	v_div_scale_f32 v18, s[2:3], v17, v17, v33
	v_rcp_f32_e32 v19, v18
	s_nop 0
	v_fma_f32 v34, -v18, v19, 1.0
	v_fmac_f32_e32 v19, v34, v19
	v_div_scale_f32 v34, vcc, v33, v17, v33
	v_mul_f32_e32 v35, v34, v19
	v_fma_f32 v40, -v18, v35, v34
	v_fmac_f32_e32 v35, v40, v19
	v_fma_f32 v18, -v18, v35, v34
	v_div_fmas_f32 v18, v18, v19, v35
	v_div_fixup_f32 v17, v18, v17, v33
	v_div_scale_f32 v18, s[2:3], v16, v16, v32
	v_rcp_f32_e32 v19, v18
	s_nop 0
	v_fma_f32 v33, -v18, v19, 1.0
	v_fmac_f32_e32 v19, v33, v19
	v_div_scale_f32 v33, vcc, v32, v16, v32
	v_mul_f32_e32 v34, v33, v19
	v_fma_f32 v35, -v18, v34, v33
	v_fmac_f32_e32 v34, v35, v19
	v_fma_f32 v18, -v18, v34, v33
	v_div_fmas_f32 v18, v18, v19, v34
	v_div_fixup_f32 v16, v18, v16, v32
	v_pk_mul_f32 v[14:15], v[14:15], v[16:17]
	v_pk_mul_f32 v[32:33], v[38:39], v[2:3] op_sel_hi:[1,0]
	v_cvt_pk_bf16_f32 v13, v14, v15
	global_store_dwordx2 v[144:145], v[12:13], off offset:128
	global_load_dwordx2 v[202:203], v[70:71], off offset:2240
	global_load_dwordx4 v[212:215], v73, s[38:39] offset:384
	s_nop 0
	s_waitcnt vmcnt(10)
	v_lshlrev_b32_e32 v34, 16, v204
	v_and_b32_e32 v16, 0xffff0000, v204
	v_mul_f32_e32 v18, 0xbfb8aa3b, v34
	v_mul_f32_e32 v19, 0xbfb8aa3b, v16
	v_exp_f32_e32 v18, v18
	v_exp_f32_e32 v19, v19
	s_waitcnt vmcnt(9)
	v_pk_mul_f32 v[12:13], v[32:33], v[216:217]
	v_pk_add_f32 v[18:19], v[18:19], 1.0 op_sel_hi:[1, 0]
	s_nop 0
	v_div_scale_f32 v32, s[2:3], v19, v19, v16
	v_rcp_f32_e32 v33, v32
	s_nop 0
	v_fma_f32 v35, -v32, v33, 1.0
	v_fmac_f32_e32 v33, v35, v33
	v_div_scale_f32 v35, vcc, v16, v19, v16
	v_mul_f32_e32 v38, v35, v33
	v_fma_f32 v39, -v32, v38, v35
	v_fmac_f32_e32 v38, v39, v33
	v_fma_f32 v32, -v32, v38, v35
	v_div_fmas_f32 v32, v32, v33, v38
	v_div_fixup_f32 v19, v32, v19, v16
	v_div_scale_f32 v16, s[2:3], v18, v18, v34
	v_rcp_f32_e32 v32, v16
	s_nop 0
	v_fma_f32 v33, -v16, v32, 1.0
	v_fmac_f32_e32 v32, v33, v32
	v_div_scale_f32 v33, vcc, v34, v18, v34
	v_mul_f32_e32 v35, v33, v32
	v_fma_f32 v38, -v16, v35, v33
	v_fmac_f32_e32 v35, v38, v32
	v_fma_f32 v16, -v16, v35, v33
	v_div_fmas_f32 v16, v16, v32, v35
	v_lshlrev_b32_e32 v32, 16, v205
	v_and_b32_e32 v33, 0xffff0000, v205
	v_div_fixup_f32 v18, v16, v18, v34
	v_mul_f32_e32 v16, 0xbfb8aa3b, v32
	v_mul_f32_e32 v17, 0xbfb8aa3b, v33
	v_exp_f32_e32 v16, v16
	v_exp_f32_e32 v17, v17
	v_pk_mul_f32 v[12:13], v[12:13], v[18:19]
	v_pk_mul_f32 v[18:19], v[36:37], v[2:3] op_sel_hi:[1, 0]
	v_cvt_pk_bf16_f32 v12, v12, v13
	v_pk_add_f32 v[16:17], v[16:17], 1.0 op_sel_hi:[1, 0]
	v_pk_mul_f32 v[14:15], v[18:19], v[218:219]
	v_div_scale_f32 v18, s[2:3], v17, v17, v33
	v_rcp_f32_e32 v19, v18
	s_nop 0
	v_fma_f32 v34, -v18, v19, 1.0
	v_fmac_f32_e32 v19, v34, v19
	v_div_scale_f32 v34, vcc, v33, v17, v33
	v_mul_f32_e32 v35, v34, v19
	v_fma_f32 v36, -v18, v35, v34
	v_fmac_f32_e32 v35, v36, v19
	v_fma_f32 v18, -v18, v35, v34
	v_div_fmas_f32 v18, v18, v19, v35
	v_div_fixup_f32 v17, v18, v17, v33
	v_div_scale_f32 v18, s[2:3], v16, v16, v32
	v_rcp_f32_e32 v19, v18
	s_nop 0
	v_fma_f32 v33, -v18, v19, 1.0
	v_fmac_f32_e32 v19, v33, v19
	v_div_scale_f32 v33, vcc, v32, v16, v32
	v_mul_f32_e32 v34, v33, v19
	v_fma_f32 v35, -v18, v34, v33
	v_fmac_f32_e32 v34, v35, v19
	v_fma_f32 v18, -v18, v34, v33
	v_div_fmas_f32 v18, v18, v19, v34
	v_div_fixup_f32 v16, v18, v16, v32
	v_pk_mul_f32 v[14:15], v[14:15], v[16:17]
	s_nop 0
	v_cvt_pk_bf16_f32 v13, v14, v15
	global_store_dwordx2 v[144:145], v[12:13], off offset:144
	global_load_dwordx2 v[204:205], v[70:71], off offset:2256
	global_load_dwordx4 v[216:219], v73, s[38:39] offset:416
	s_nop 0
	s_waitcnt vmcnt(10)
	v_lshlrev_b32_e32 v32, 16, v206
	v_and_b32_e32 v16, 0xffff0000, v206
	v_mul_f32_e32 v18, 0xbfb8aa3b, v32
	v_mul_f32_e32 v19, 0xbfb8aa3b, v16
	v_exp_f32_e32 v18, v18
	v_exp_f32_e32 v19, v19
	s_waitcnt vmcnt(9)
	v_pk_mul_f32 v[12:13], v[28:29], v[220:221]
	v_pk_add_f32 v[18:19], v[18:19], 1.0 op_sel_hi:[1, 0]
	s_nop 0
	v_div_scale_f32 v28, s[2:3], v19, v19, v16
	v_rcp_f32_e32 v29, v28
	s_nop 0
	v_fma_f32 v33, -v28, v29, 1.0
	v_fmac_f32_e32 v29, v33, v29
	v_div_scale_f32 v33, vcc, v16, v19, v16
	v_mul_f32_e32 v34, v33, v29
	v_fma_f32 v35, -v28, v34, v33
	v_fmac_f32_e32 v34, v35, v29
	v_fma_f32 v28, -v28, v34, v33
	v_div_fmas_f32 v28, v28, v29, v34
	v_div_fixup_f32 v19, v28, v19, v16
	v_div_scale_f32 v16, s[2:3], v18, v18, v32
	v_rcp_f32_e32 v28, v16
	s_nop 0
	v_fma_f32 v29, -v16, v28, 1.0
	v_fmac_f32_e32 v28, v29, v28
	v_div_scale_f32 v29, vcc, v32, v18, v32
	v_mul_f32_e32 v33, v29, v28
	v_fma_f32 v34, -v16, v33, v29
	v_fmac_f32_e32 v33, v34, v28
	v_fma_f32 v16, -v16, v33, v29
	v_div_fmas_f32 v16, v16, v28, v33
	v_lshlrev_b32_e32 v28, 16, v207
	v_and_b32_e32 v29, 0xffff0000, v207
	v_div_fixup_f32 v18, v16, v18, v32
	v_mul_f32_e32 v16, 0xbfb8aa3b, v28
	v_mul_f32_e32 v17, 0xbfb8aa3b, v29
	v_exp_f32_e32 v16, v16
	v_exp_f32_e32 v17, v17
	v_pk_mul_f32 v[12:13], v[12:13], v[18:19]
	v_pk_mul_f32 v[18:19], v[30:31], v[2:3] op_sel_hi:[1, 0]
	v_cvt_pk_bf16_f32 v12, v12, v13
	v_pk_add_f32 v[16:17], v[16:17], 1.0 op_sel_hi:[1, 0]
	v_pk_mul_f32 v[14:15], v[18:19], v[222:223]
	v_div_scale_f32 v18, s[2:3], v17, v17, v29
	v_rcp_f32_e32 v19, v18
	s_nop 0
	v_fma_f32 v30, -v18, v19, 1.0
	v_fmac_f32_e32 v19, v30, v19
	v_div_scale_f32 v30, vcc, v29, v17, v29
	v_mul_f32_e32 v31, v30, v19
	v_fma_f32 v32, -v18, v31, v30
	v_fmac_f32_e32 v31, v32, v19
	v_fma_f32 v18, -v18, v31, v30
	v_div_fmas_f32 v18, v18, v19, v31
	v_div_fixup_f32 v17, v18, v17, v29
	v_div_scale_f32 v18, s[2:3], v16, v16, v28
	v_rcp_f32_e32 v19, v18
	s_nop 0
	v_fma_f32 v29, -v18, v19, 1.0
	v_fmac_f32_e32 v19, v29, v19
	v_div_scale_f32 v29, vcc, v28, v16, v28
	v_mul_f32_e32 v30, v29, v19
	v_fma_f32 v31, -v18, v30, v29
	v_fmac_f32_e32 v30, v31, v19
	v_fma_f32 v18, -v18, v30, v29
	v_div_fmas_f32 v18, v18, v19, v30
	v_div_fixup_f32 v16, v18, v16, v28
	v_pk_mul_f32 v[14:15], v[14:15], v[16:17]
	s_nop 0
	v_cvt_pk_bf16_f32 v13, v14, v15
	global_store_dwordx2 v[144:145], v[12:13], off offset:160
	global_load_dwordx2 v[206:207], v[70:71], off offset:2272
	global_load_dwordx4 v[220:223], v73, s[38:39] offset:448
	s_nop 0
	s_waitcnt vmcnt(10)
	v_lshlrev_b32_e32 v28, 16, v208
	v_and_b32_e32 v16, 0xffff0000, v208
	v_mul_f32_e32 v18, 0xbfb8aa3b, v28
	v_mul_f32_e32 v19, 0xbfb8aa3b, v16
	v_exp_f32_e32 v18, v18
	v_exp_f32_e32 v19, v19
	s_waitcnt vmcnt(9)
	v_pk_mul_f32 v[12:13], v[26:27], v[236:237]
	v_pk_add_f32 v[18:19], v[18:19], 1.0 op_sel_hi:[1, 0]
	s_nop 0
	v_div_scale_f32 v26, s[2:3], v19, v19, v16
	v_rcp_f32_e32 v27, v26
	s_nop 0
	v_fma_f32 v29, -v26, v27, 1.0
	v_fmac_f32_e32 v27, v29, v27
	v_div_scale_f32 v29, vcc, v16, v19, v16
	v_mul_f32_e32 v30, v29, v27
	v_fma_f32 v31, -v26, v30, v29
	v_fmac_f32_e32 v30, v31, v27
	v_fma_f32 v26, -v26, v30, v29
	v_div_fmas_f32 v26, v26, v27, v30
	v_div_fixup_f32 v19, v26, v19, v16
	v_div_scale_f32 v16, s[2:3], v18, v18, v28
	v_rcp_f32_e32 v26, v16
	s_nop 0
	v_fma_f32 v27, -v16, v26, 1.0
	v_fmac_f32_e32 v26, v27, v26
	v_div_scale_f32 v27, vcc, v28, v18, v28
	v_mul_f32_e32 v29, v27, v26
	v_fma_f32 v30, -v16, v29, v27
	v_fmac_f32_e32 v29, v30, v26
	v_fma_f32 v16, -v16, v29, v27
	v_div_fmas_f32 v16, v16, v26, v29
	v_lshlrev_b32_e32 v26, 16, v209
	v_and_b32_e32 v27, 0xffff0000, v209
	v_div_fixup_f32 v18, v16, v18, v28
	v_mul_f32_e32 v16, 0xbfb8aa3b, v26
	v_mul_f32_e32 v17, 0xbfb8aa3b, v27
	v_exp_f32_e32 v16, v16
	v_exp_f32_e32 v17, v17
	v_pk_mul_f32 v[12:13], v[12:13], v[18:19]
	v_pk_mul_f32 v[18:19], v[24:25], v[2:3] op_sel_hi:[1, 0]
	v_cvt_pk_bf16_f32 v12, v12, v13
	v_pk_add_f32 v[16:17], v[16:17], 1.0 op_sel_hi:[1, 0]
	v_pk_mul_f32 v[14:15], v[18:19], v[238:239]
	v_div_scale_f32 v18, s[2:3], v17, v17, v27
	v_rcp_f32_e32 v19, v18
	s_nop 0
	v_fma_f32 v24, -v18, v19, 1.0
	v_fmac_f32_e32 v19, v24, v19
	v_div_scale_f32 v24, vcc, v27, v17, v27
	v_mul_f32_e32 v25, v24, v19
	v_fma_f32 v28, -v18, v25, v24
	v_fmac_f32_e32 v25, v28, v19
	v_fma_f32 v18, -v18, v25, v24
	v_div_fmas_f32 v18, v18, v19, v25
	v_div_fixup_f32 v17, v18, v17, v27
	v_div_scale_f32 v18, s[2:3], v16, v16, v26
	v_rcp_f32_e32 v19, v18
	s_nop 0
	v_fma_f32 v24, -v18, v19, 1.0
	v_fmac_f32_e32 v19, v24, v19
	v_div_scale_f32 v24, vcc, v26, v16, v26
	v_mul_f32_e32 v25, v24, v19
	v_fma_f32 v27, -v18, v25, v24
	v_fmac_f32_e32 v25, v27, v19
	v_fma_f32 v18, -v18, v25, v24
	v_div_fmas_f32 v18, v18, v19, v25
	v_div_fixup_f32 v16, v18, v16, v26
	v_pk_mul_f32 v[14:15], v[14:15], v[16:17]
	s_nop 0
	v_cvt_pk_bf16_f32 v13, v14, v15
	global_store_dwordx2 v[144:145], v[12:13], off offset:176
	global_load_dwordx2 v[208:209], v[70:71], off offset:2288
	global_load_dwordx4 v[236:239], v73, s[38:39] offset:480
	s_nop 0
	s_waitcnt vmcnt(10)
	v_lshlrev_b32_e32 v24, 16, v202
	v_and_b32_e32 v16, 0xffff0000, v202
	v_mul_f32_e32 v18, 0xbfb8aa3b, v24
	v_mul_f32_e32 v19, 0xbfb8aa3b, v16
	v_exp_f32_e32 v18, v18
	v_exp_f32_e32 v19, v19
	s_waitcnt vmcnt(9)
	v_pk_mul_f32 v[12:13], v[22:23], v[212:213]
	v_pk_add_f32 v[18:19], v[18:19], 1.0 op_sel_hi:[1, 0]
	s_nop 0
	v_div_scale_f32 v22, s[2:3], v19, v19, v16
	v_rcp_f32_e32 v23, v22
	s_nop 0
	v_fma_f32 v25, -v22, v23, 1.0
	v_fmac_f32_e32 v23, v25, v23
	v_div_scale_f32 v25, vcc, v16, v19, v16
	v_mul_f32_e32 v26, v25, v23
	v_fma_f32 v27, -v22, v26, v25
	v_fmac_f32_e32 v26, v27, v23
	v_fma_f32 v22, -v22, v26, v25
	v_div_fmas_f32 v22, v22, v23, v26
	v_div_fixup_f32 v19, v22, v19, v16
	v_div_scale_f32 v16, s[2:3], v18, v18, v24
	v_rcp_f32_e32 v22, v16
	s_nop 0
	v_fma_f32 v23, -v16, v22, 1.0
	v_fmac_f32_e32 v22, v23, v22
	v_div_scale_f32 v23, vcc, v24, v18, v24
	v_mul_f32_e32 v25, v23, v22
	v_fma_f32 v26, -v16, v25, v23
	v_fmac_f32_e32 v25, v26, v22
	v_fma_f32 v16, -v16, v25, v23
	v_div_fmas_f32 v16, v16, v22, v25
	v_lshlrev_b32_e32 v22, 16, v203
	v_and_b32_e32 v23, 0xffff0000, v203
	v_div_fixup_f32 v18, v16, v18, v24
	v_mul_f32_e32 v16, 0xbfb8aa3b, v22
	v_mul_f32_e32 v17, 0xbfb8aa3b, v23
	v_exp_f32_e32 v16, v16
	v_exp_f32_e32 v17, v17
	v_pk_mul_f32 v[12:13], v[12:13], v[18:19]
	v_pk_mul_f32 v[18:19], v[20:21], v[2:3] op_sel_hi:[1, 0]
	v_cvt_pk_bf16_f32 v12, v12, v13
	v_pk_add_f32 v[16:17], v[16:17], 1.0 op_sel_hi:[1, 0]
	v_pk_mul_f32 v[14:15], v[18:19], v[214:215]
	v_div_scale_f32 v18, s[2:3], v17, v17, v23
	v_rcp_f32_e32 v19, v18
	s_nop 0
	v_fma_f32 v20, -v18, v19, 1.0
	v_fmac_f32_e32 v19, v20, v19
	v_div_scale_f32 v20, vcc, v23, v17, v23
	v_mul_f32_e32 v21, v20, v19
	v_fma_f32 v24, -v18, v21, v20
	v_fmac_f32_e32 v21, v24, v19
	v_fma_f32 v18, -v18, v21, v20
	v_div_fmas_f32 v18, v18, v19, v21
	v_div_fixup_f32 v17, v18, v17, v23
	v_div_scale_f32 v18, s[2:3], v16, v16, v22
	v_rcp_f32_e32 v19, v18
	s_nop 0
	v_fma_f32 v20, -v18, v19, 1.0
	v_fmac_f32_e32 v19, v20, v19
	v_div_scale_f32 v20, vcc, v22, v16, v22
	v_mul_f32_e32 v21, v20, v19
	v_fma_f32 v23, -v18, v21, v20
	v_fmac_f32_e32 v21, v23, v19
	v_fma_f32 v18, -v18, v21, v20
	v_div_fmas_f32 v18, v18, v19, v21
	v_div_fixup_f32 v16, v18, v16, v22
	v_pk_mul_f32 v[14:15], v[14:15], v[16:17]
	s_nop 0
	v_cvt_pk_bf16_f32 v13, v14, v15
	global_store_dwordx2 v[144:145], v[12:13], off offset:192
	s_nop 0
	s_waitcnt vmcnt(8)
	v_lshlrev_b32_e32 v20, 16, v204
	v_and_b32_e32 v16, 0xffff0000, v204
	v_mul_f32_e32 v18, 0xbfb8aa3b, v20
	s_waitcnt vmcnt(7)
	v_pk_mul_f32 v[8:9], v[8:9], v[216:217]
	v_mul_f32_e32 v12, 0xbfb8aa3b, v16
	v_exp_f32_e32 v18, v18
	v_exp_f32_e32 v19, v12
	v_pk_mul_f32 v[10:11], v[10:11], v[218:219]
	v_pk_add_f32 v[12:13], v[18:19], 1.0 op_sel_hi:[1, 0]
	s_nop 0
	v_div_scale_f32 v18, s[2:3], v13, v13, v16
	v_rcp_f32_e32 v19, v18
	s_nop 0
	v_fma_f32 v21, -v18, v19, 1.0
	v_fmac_f32_e32 v19, v21, v19
	v_div_scale_f32 v21, vcc, v16, v13, v16
	v_mul_f32_e32 v22, v21, v19
	v_fma_f32 v23, -v18, v22, v21
	v_fmac_f32_e32 v22, v23, v19
	v_fma_f32 v18, -v18, v22, v21
	v_div_fmas_f32 v18, v18, v19, v22
	v_div_fixup_f32 v13, v18, v13, v16
	v_div_scale_f32 v16, s[2:3], v12, v12, v20
	v_rcp_f32_e32 v18, v16
	s_nop 0
	v_fma_f32 v19, -v16, v18, 1.0
	v_fmac_f32_e32 v18, v19, v18
	v_div_scale_f32 v19, vcc, v20, v12, v20
	v_mul_f32_e32 v21, v19, v18
	v_fma_f32 v22, -v16, v21, v19
	v_fmac_f32_e32 v21, v22, v18
	v_fma_f32 v16, -v16, v21, v19
	v_div_fmas_f32 v16, v16, v18, v21
	v_div_fixup_f32 v12, v16, v12, v20
	v_lshlrev_b32_e32 v16, 16, v205
	v_and_b32_e32 v17, 0xffff0000, v205
	v_pk_mul_f32 v[8:9], v[8:9], v[12:13]
	v_mul_f32_e32 v12, 0xbfb8aa3b, v16
	v_mul_f32_e32 v13, 0xbfb8aa3b, v17
	v_exp_f32_e32 v12, v12
	v_exp_f32_e32 v13, v13
	v_cvt_pk_bf16_f32 v8, v8, v9
	v_pk_add_f32 v[12:13], v[12:13], 1.0 op_sel_hi:[1, 0]
	s_nop 0
	v_div_scale_f32 v14, s[2:3], v13, v13, v17
	v_rcp_f32_e32 v15, v14
	s_nop 0
	v_fma_f32 v18, -v14, v15, 1.0
	v_fmac_f32_e32 v15, v18, v15
	v_div_scale_f32 v18, vcc, v17, v13, v17
	v_mul_f32_e32 v19, v18, v15
	v_fma_f32 v20, -v14, v19, v18
	v_fmac_f32_e32 v19, v20, v15
	v_fma_f32 v14, -v14, v19, v18
	v_div_fmas_f32 v14, v14, v15, v19
	v_div_fixup_f32 v13, v14, v13, v17
	v_div_scale_f32 v14, s[2:3], v12, v12, v16
	v_rcp_f32_e32 v15, v14
	s_nop 0
	v_fma_f32 v17, -v14, v15, 1.0
	v_fmac_f32_e32 v15, v17, v15
	v_div_scale_f32 v17, vcc, v16, v12, v16
	v_mul_f32_e32 v18, v17, v15
	v_fma_f32 v19, -v14, v18, v17
	v_fmac_f32_e32 v18, v19, v15
	v_fma_f32 v14, -v14, v18, v17
	v_div_fmas_f32 v14, v14, v15, v18
	v_div_fixup_f32 v12, v14, v12, v16
	v_pk_mul_f32 v[10:11], v[10:11], v[12:13]
	s_nop 0
	v_cvt_pk_bf16_f32 v9, v10, v11
	global_store_dwordx2 v[144:145], v[8:9], off offset:208
	s_nop 0
	s_waitcnt vmcnt(6)
	v_lshlrev_b32_e32 v16, 16, v206
	v_and_b32_e32 v12, 0xffff0000, v206
	v_mul_f32_e32 v14, 0xbfb8aa3b, v16
	s_waitcnt vmcnt(5)
	v_pk_mul_f32 v[6:7], v[6:7], v[220:221]
	v_mul_f32_e32 v8, 0xbfb8aa3b, v12
	v_exp_f32_e32 v14, v14
	v_exp_f32_e32 v15, v8
	v_pk_mul_f32 v[4:5], v[4:5], v[222:223]
	v_pk_add_f32 v[8:9], v[14:15], 1.0 op_sel_hi:[1, 0]
	s_nop 0
	v_div_scale_f32 v14, s[2:3], v9, v9, v12
	v_rcp_f32_e32 v15, v14
	s_nop 0
	v_fma_f32 v17, -v14, v15, 1.0
	v_fmac_f32_e32 v15, v17, v15
	v_div_scale_f32 v17, vcc, v12, v9, v12
	v_mul_f32_e32 v18, v17, v15
	v_fma_f32 v19, -v14, v18, v17
	v_fmac_f32_e32 v18, v19, v15
	v_fma_f32 v14, -v14, v18, v17
	v_div_fmas_f32 v14, v14, v15, v18
	v_div_fixup_f32 v9, v14, v9, v12
	v_div_scale_f32 v12, s[2:3], v8, v8, v16
	v_rcp_f32_e32 v14, v12
	s_nop 0
	v_fma_f32 v15, -v12, v14, 1.0
	v_fmac_f32_e32 v14, v15, v14
	v_div_scale_f32 v15, vcc, v16, v8, v16
	v_mul_f32_e32 v17, v15, v14
	v_fma_f32 v18, -v12, v17, v15
	v_fmac_f32_e32 v17, v18, v14
	v_fma_f32 v12, -v12, v17, v15
	v_div_fmas_f32 v12, v12, v14, v17
	v_div_fixup_f32 v8, v12, v8, v16
	v_lshlrev_b32_e32 v12, 16, v207
	v_and_b32_e32 v13, 0xffff0000, v207
	v_pk_mul_f32 v[6:7], v[6:7], v[8:9]
	v_mul_f32_e32 v8, 0xbfb8aa3b, v12
	v_mul_f32_e32 v9, 0xbfb8aa3b, v13
	v_exp_f32_e32 v8, v8
	v_exp_f32_e32 v9, v9
	v_cvt_pk_bf16_f32 v6, v6, v7
	v_pk_add_f32 v[8:9], v[8:9], 1.0 op_sel_hi:[1, 0]
	s_nop 0
	v_div_scale_f32 v10, s[2:3], v9, v9, v13
	v_rcp_f32_e32 v11, v10
	s_nop 0
	v_fma_f32 v14, -v10, v11, 1.0
	v_fmac_f32_e32 v11, v14, v11
	v_div_scale_f32 v14, vcc, v13, v9, v13
	v_mul_f32_e32 v15, v14, v11
	v_fma_f32 v16, -v10, v15, v14
	v_fmac_f32_e32 v15, v16, v11
	v_fma_f32 v10, -v10, v15, v14
	v_div_fmas_f32 v10, v10, v11, v15
	v_div_fixup_f32 v9, v10, v9, v13
	v_div_scale_f32 v10, s[2:3], v8, v8, v12
	v_rcp_f32_e32 v11, v10
	s_nop 0
	v_fma_f32 v13, -v10, v11, 1.0
	v_fmac_f32_e32 v11, v13, v11
	v_div_scale_f32 v13, vcc, v12, v8, v12
	v_mul_f32_e32 v14, v13, v11
	v_fma_f32 v15, -v10, v14, v13
	v_fmac_f32_e32 v14, v15, v11
	v_fma_f32 v10, -v10, v14, v13
	v_div_fmas_f32 v10, v10, v11, v14
	v_div_fixup_f32 v8, v10, v8, v12
	v_pk_mul_f32 v[4:5], v[4:5], v[8:9]
	v_pk_mul_f32 v[12:13], v[68:69], v[2:3] op_sel_hi:[1,0]
	v_cvt_pk_bf16_f32 v7, v4, v5
	global_store_dwordx2 v[144:145], v[6:7], off offset:224
	s_waitcnt vmcnt(4)
	v_lshlrev_b32_e32 v14, 16, v208
	v_and_b32_e32 v8, 0xffff0000, v208
	v_mul_f32_e32 v10, 0xbfb8aa3b, v14
	v_mul_f32_e32 v11, 0xbfb8aa3b, v8
	v_exp_f32_e32 v10, v10
	v_exp_f32_e32 v11, v11
	s_waitcnt vmcnt(3)
	v_pk_mul_f32 v[4:5], v[12:13], v[236:237]
	v_pk_add_f32 v[10:11], v[10:11], 1.0 op_sel_hi:[1, 0]
	v_pk_mul_f32 v[0:1], v[0:1], v[238:239]
	v_div_scale_f32 v12, s[2:3], v11, v11, v8
	v_rcp_f32_e32 v13, v12
	s_nop 0
	v_fma_f32 v15, -v12, v13, 1.0
	v_fmac_f32_e32 v13, v15, v13
	v_div_scale_f32 v15, vcc, v8, v11, v8
	v_mul_f32_e32 v16, v15, v13
	v_fma_f32 v17, -v12, v16, v15
	v_fmac_f32_e32 v16, v17, v13
	v_fma_f32 v12, -v12, v16, v15
	v_div_fmas_f32 v12, v12, v13, v16
	v_div_fixup_f32 v11, v12, v11, v8
	v_div_scale_f32 v8, s[2:3], v10, v10, v14
	v_rcp_f32_e32 v12, v8
	s_nop 0
	v_fma_f32 v13, -v8, v12, 1.0
	v_fmac_f32_e32 v12, v13, v12
	v_div_scale_f32 v13, vcc, v14, v10, v14
	v_mul_f32_e32 v15, v13, v12
	v_fma_f32 v16, -v8, v15, v13
	v_fmac_f32_e32 v15, v16, v12
	v_fma_f32 v8, -v8, v15, v13
	v_div_fmas_f32 v8, v8, v12, v15
	v_div_fixup_f32 v10, v8, v10, v14
	v_pk_mul_f32 v[4:5], v[4:5], v[10:11]
	v_lshlrev_b32_e32 v10, 16, v209
	v_and_b32_e32 v11, 0xffff0000, v209
	v_mul_f32_e32 v8, 0xbfb8aa3b, v10
	v_mul_f32_e32 v2, 0xbfb8aa3b, v11
	v_exp_f32_e32 v8, v8
	v_exp_f32_e32 v9, v2
	v_cvt_pk_bf16_f32 v4, v4, v5
	v_pk_add_f32 v[6:7], v[8:9], 1.0 op_sel_hi:[1, 0]
	s_nop 0
	v_div_scale_f32 v2, s[2:3], v7, v7, v11
	v_rcp_f32_e32 v8, v2
	s_nop 0
	v_fma_f32 v9, -v2, v8, 1.0
	v_fmac_f32_e32 v8, v9, v8
	v_div_scale_f32 v9, vcc, v11, v7, v11
	v_mul_f32_e32 v12, v9, v8
	v_fma_f32 v13, -v2, v12, v9
	v_fmac_f32_e32 v12, v13, v8
	v_fma_f32 v2, -v2, v12, v9
	v_div_fmas_f32 v2, v2, v8, v12
	v_div_fixup_f32 v7, v2, v7, v11
	v_div_scale_f32 v2, s[2:3], v6, v6, v10
	v_rcp_f32_e32 v8, v2
	s_mov_b64 s[2:3], 0
	v_fma_f32 v9, -v2, v8, 1.0
	v_fmac_f32_e32 v8, v9, v8
	v_div_scale_f32 v9, vcc, v10, v6, v10
	v_mul_f32_e32 v11, v9, v8
	v_fma_f32 v12, -v2, v11, v9
	v_fmac_f32_e32 v11, v12, v8
	v_fma_f32 v2, -v2, v11, v9
	v_div_fmas_f32 v2, v2, v8, v11
	v_div_fixup_f32 v6, v2, v6, v10
	v_pk_mul_f32 v[0:1], v[0:1], v[6:7]
	s_nop 0
	v_cvt_pk_bf16_f32 v5, v0, v1
	global_store_dwordx2 v[144:145], v[4:5], off offset:240
